# grid barrier at 3 of 4 sites hand-written: last XCD arriver publishes every XCD generation word directly (one poll hop instead of two), float reciprocal for the generation quotient
# baseline (speedup 1.0000x reference)
.LBB0_158:
	s_or_b64 exec, exec, s[4:5]
	s_cmp_eq_u64 s[24:25], 0
	s_cselect_b64 s[92:93], -1, 0
	s_add_u32 s4, s36, 0x1a00000
	s_addc_u32 s5, s37, 0
	v_writelane_b32 v254, s4, 1
	s_lshl_b32 s94, s34, 11
	s_add_u32 s3, s36, 0x1c00000
	v_writelane_b32 v254, s5, 2
	v_writelane_b32 v254, s3, 3
	s_addc_u32 s3, s37, 0
	s_cmpk_lt_i32 s2, 0xb00
	s_cselect_b64 s[4:5], -1, 0
	s_ashr_i32 s83, s2, 31
	v_writelane_b32 v254, s3, 4
	s_lshr_b32 s3, s83, 29
	s_add_i32 s3, s2, s3
	s_ashr_i32 s9, s3, 3
	s_and_b32 s3, s3, -8
	s_sub_i32 s6, s2, s3
	v_writelane_b32 v254, s4, 5
	s_cmp_gt_i32 s6, -1
	s_mul_i32 s35, s35, s34
	v_writelane_b32 v254, s5, 6
	s_cselect_b64 s[4:5], -1, 0
	s_ashr_i32 s84, s34, 31
	s_add_u32 s60, s36, 0x7200000
	v_writelane_b32 v254, s4, 7
	s_addc_u32 s61, s37, 0
	v_mov_b32_e32 v238, 0x358637bd
	v_writelane_b32 v254, s5, 8
	s_add_u32 s4, s36, 0x12c00000
	s_addc_u32 s5, s37, 0
	v_writelane_b32 v254, s4, 9
	v_mov_b32_e32 v239, 1
	v_mbcnt_hi_u32_b32 v242, -1, v26
	v_writelane_b32 v254, s5, 10
	s_add_u32 s4, s36, 0x12600000
	s_addc_u32 s5, s37, 0
	v_writelane_b32 v254, s4, 11
	v_mov_b32_e32 v243, 0xff800000
	v_mov_b64_e32 v[184:185], 0x1ff
	v_writelane_b32 v254, s5, 12
	s_add_u32 s4, s36, 0x12900000
	s_addc_u32 s5, s37, 0
	s_add_u32 s98, s36, 0x200
	s_addc_u32 s99, s37, 0
	s_add_u32 s62, s36, 0x1000
	s_addc_u32 s63, s37, 0
	s_add_u32 s66, s36, 0x1100
	s_addc_u32 s67, s37, 0
	s_add_u32 s70, s36, 0x1200
	s_addc_u32 s71, s37, 0
	s_add_u32 s78, s36, 0x1300
	v_writelane_b32 v254, s4, 13
	s_addc_u32 s79, s37, 0
	v_mov_b64_e32 v[186:187], 0x200
	v_writelane_b32 v254, s5, 14
	s_add_u32 s4, s36, 0x3400
	s_addc_u32 s5, s37, 0
	s_add_u32 s80, s36, 0x3500
	s_addc_u32 s81, s37, 0
	s_lshl_b32 s3, s2, 4
	v_writelane_b32 v254, s4, 15
	s_and_b32 s3, s3, 0x70
	s_movk_i32 s85, 0x1800
	v_writelane_b32 v254, s5, 16
	s_add_u32 s4, s36, 0x100000
	v_writelane_b32 v254, s3, 17
	s_addc_u32 s5, s37, 0
	v_writelane_b32 v254, s4, 18
	s_mov_b32 s82, 0x3e38aa3b
	s_mov_b64 s[40:41], 0
	v_writelane_b32 v254, s5, 19
	s_add_u32 s4, s36, 0x400000
	s_addc_u32 s5, s37, 0
	s_add_u32 s10, s36, 0x13200000
	s_addc_u32 s11, s37, 0
	v_writelane_b32 v254, s4, 20
	s_cmpk_lt_i32 s2, 0x100
	s_mov_b32 s43, 0
	v_writelane_b32 v254, s5, 21
	s_cselect_b64 s[4:5], -1, 0
	s_lshl_b32 s12, s2, 7
	v_writelane_b32 v254, s4, 22
	s_ashr_i32 s13, s12, 31
	s_mov_b64 s[38:39], 0x80
	v_writelane_b32 v254, s5, 23
	s_lshl_b64 s[4:5], s[12:13], 1
	s_add_u32 s4, s10, s4
	v_writelane_b32 v254, s10, 24
	s_addc_u32 s5, s11, s5
	s_add_i32 s3, s33, -7
	v_writelane_b32 v254, s11, 25
	v_writelane_b32 v254, s4, 26
	s_add_u32 s7, s36, 0xc200000
	s_addc_u32 s8, s37, 0
	v_writelane_b32 v254, s5, 27
	v_writelane_b32 v254, s3, 28
	v_writelane_b32 v254, s7, 29
	s_add_u32 s4, s36, 0xd200000
	v_writelane_b32 v254, s8, 30
	s_addc_u32 s5, s37, 0
	v_writelane_b32 v254, s4, 31
	s_cmpk_lt_i32 s2, 0x400
	s_mov_b32 s96, 0x3dd2d3e7
	v_writelane_b32 v254, s5, 32
	s_cselect_b64 s[4:5], -1, 0
	v_writelane_b32 v254, s4, 33
	s_lshl_b32 s3, s2, 5
	s_and_b32 s10, s3, 0xfffff000
	v_writelane_b32 v254, s5, 34
	v_writelane_b32 v254, s3, 35
	v_writelane_b32 v254, s12, 36
	s_and_b32 s3, s12, 0xf80
	s_mov_b32 s4, s10
	v_writelane_b32 v254, s13, 37
	v_writelane_b32 v254, s3, 38
	s_addk_i32 s3, 0xff80
	v_writelane_b32 v254, s3, 39
	s_lshl_b32 s3, s2, 1
	s_and_b32 s12, s3, 0xc0
	s_or_b32 s3, s10, 64
	v_writelane_b32 v254, s3, 40
	s_or_b32 s3, s10, 0xc0
	v_writelane_b32 v254, s3, 41
	s_ashr_i32 s11, s10, 31
	v_writelane_b32 v254, s4, 42
	s_mov_b32 s88, 0xc0135761
	s_nop 0
	v_writelane_b32 v254, s5, 43
	s_lshl_b64 s[4:5], s[10:11], 1
	s_add_u32 s4, s7, s4
	s_addc_u32 s5, s8, s5
	v_writelane_b32 v254, s4, 44
	s_nop 1
	v_writelane_b32 v254, s5, 45
	s_add_u32 s4, s36, 0x2700000
	s_addc_u32 s5, s37, 0
	v_writelane_b32 v254, s4, 46
	s_cmpk_lt_i32 s2, 0x200
	s_nop 0
	v_writelane_b32 v254, s5, 47
	s_cselect_b64 s[4:5], -1, 0
	v_writelane_b32 v254, s4, 48
	s_cmpk_gt_i32 s2, 0x1ff
	s_nop 0
	v_writelane_b32 v254, s5, 49
	s_cselect_b64 s[4:5], -1, 0
	s_lshl_b32 s3, s6, 6
	s_add_u32 s52, s36, 0x1a80000
	v_writelane_b32 v254, s4, 50
	s_addc_u32 s53, s37, 0
	s_cmp_lt_i32 s6, 0
	v_writelane_b32 v254, s5, 51
	s_movk_i32 s5, 0x161
	s_cselect_b32 s5, s5, 0x160
	s_mul_i32 s4, s6, 0x41
	s_mul_i32 s5, s6, s5
	s_cselect_b32 s3, s4, s3
	s_add_i32 s5, s5, s9
	s_mul_hi_i32 s4, s5, 0x2e8ba2e9
	v_writelane_b32 v254, s6, 52
	s_lshr_b32 s6, s4, 31
	s_ashr_i32 s4, s4, 5
	s_add_i32 s4, s4, s6
	s_lshl_b32 s7, s4, 3
	s_mul_i32 s6, s4, 0xb0
	s_sub_i32 s4, 0x80, s7
	s_add_i32 s3, s3, s9
	s_min_i32 s8, s4, 8
	s_ashr_i32 s4, s3, 31
	s_lshr_b32 s4, s4, 27
	s_add_i32 s4, s3, s4
	s_sub_i32 s6, s5, s6
	s_ashr_i32 s5, s4, 5
	v_writelane_b32 v254, s9, 53
	s_lshl_b32 s9, s5, 3
	s_sub_i32 s5, 0x80, s9
	s_min_i32 s10, s5, 8
	s_sext_i32_i16 s5, s8
	v_cvt_f32_i32_e32 v0, s5
	v_cvt_f32_i32_e32 v1, s6
	s_andn2_b32 s4, s4, 31
	s_sub_i32 s3, s3, s4
	v_rcp_iflag_f32_e32 v2, v0
	s_xor_b32 s4, s6, s5
	s_ashr_i32 s4, s4, 30
	s_or_b32 s11, s4, 1
	v_mul_f32_e32 v2, v1, v2
	v_trunc_f32_e32 v2, v2
	v_fma_f32 v1, -v2, v0, v1
	v_cvt_i32_f32_e32 v2, v2
	v_cmp_ge_f32_e64 s[4:5], |v1|, |v0|
	s_and_b64 s[4:5], s[4:5], exec
	s_cselect_b32 s4, s11, 0
	v_readfirstlane_b32 s5, v2
	s_add_i32 s4, s5, s4
	s_sext_i32_i16 s5, s4
	s_mul_i32 s4, s4, s8
	s_sub_i32 s4, s6, s4
	s_sext_i32_i16 s4, s4
	s_add_i32 s4, s7, s4
	v_writelane_b32 v254, s4, 54
	s_lshl_b32 s4, s4, 8
	v_writelane_b32 v254, s5, 55
	s_lshl_b32 s6, s5, 8
	s_ashr_i32 s5, s4, 31
	s_lshl_b64 s[4:5], s[4:5], 11
	v_writelane_b32 v254, s4, 56
	s_ashr_i32 s7, s6, 31
	v_cvt_f32_i32_e32 v1, s3
	v_writelane_b32 v254, s5, 57
	s_lshl_b64 s[4:5], s[6:7], 11
	v_writelane_b32 v254, s4, 58
	s_nop 1
	v_writelane_b32 v254, s5, 59
	s_sext_i32_i16 s4, s10
	v_cvt_f32_i32_e32 v0, s4
	s_lshl_b32 s5, s12, 1
	s_add_u32 s6, s60, s5
	v_writelane_b32 v254, s12, 60
	v_rcp_iflag_f32_e32 v2, v0
	s_addc_u32 s7, s61, 0
	s_xor_b32 s4, s3, s4
	v_writelane_b32 v254, s6, 61
	v_mul_f32_e32 v2, v1, v2
	v_trunc_f32_e32 v2, v2
	s_ashr_i32 s4, s4, 30
	v_fma_f32 v1, -v2, v0, v1
	v_writelane_b32 v254, s7, 62
	s_or_b32 s6, s4, 1
	v_cmp_ge_f32_e64 s[4:5], |v1|, |v0|
	s_and_b64 s[4:5], s[4:5], exec
	s_load_dword s4, s[0:1], 0xb8
	v_cvt_i32_f32_e32 v0, v2
	v_mov_b32_e32 v1, 0
	s_barrier
	s_waitcnt lgkmcnt(0)
	s_mul_i32 s35, s35, s4
	s_cselect_b32 s4, s6, 0
	v_readfirstlane_b32 s5, v0
	s_add_i32 s4, s5, s4
	s_mul_i32 s5, s4, s10
	s_sub_i32 s3, s3, s5
	s_sext_i32_i16 s3, s3
	s_add_i32 s3, s9, s3
	s_lshl_b32 s6, s3, 8
	v_writelane_b32 v255, s6, 0
	s_sext_i32_i16 s4, s4
	s_ashr_i32 s95, s94, 31
	v_writelane_b32 v255, s7, 1
	v_writelane_b32 v255, s4, 2
	s_lshl_b32 s4, s4, 8
	v_writelane_b32 v255, s4, 3
	s_lshl_b64 s[86:87], s[94:95], 2
	s_lshl_b64 s[26:27], s[94:95], 1
	v_writelane_b32 v255, s5, 4
	s_add_u32 s4, s36, 0x720a000
	s_addc_u32 s5, s37, 0
	v_writelane_b32 v255, s4, 5
	v_writelane_b32 v254, s3, 63
	s_lshl_b32 s3, s34, 5
	v_writelane_b32 v255, s5, 6
	v_writelane_b32 v255, s3, 7
	s_lshl_b32 s3, s34, 7
	v_writelane_b32 v255, s3, 8
	s_add_i32 s3, 0, 0x20800
	v_writelane_b32 v255, s3, 9
	s_add_i32 s4, 0, 0x21000
	v_writelane_b32 v255, s4, 10
	s_add_i32 s4, 0, 0x21004
	v_writelane_b32 v255, s4, 11
	s_add_i32 s4, 0, 0x11000
	v_writelane_b32 v255, s4, 12
	s_add_i32 s4, 0, 0x1a400
	v_writelane_b32 v255, s4, 13
	s_add_i32 s4, 0, 0x19800
	v_writelane_b32 v255, s4, 14
	v_writelane_b32 v255, s76, 15
	s_mov_b32 s4, s94
	s_movk_i32 s95, 0xc00
	v_writelane_b32 v255, s77, 16
	v_writelane_b32 v255, s92, 17
	s_movk_i32 s3, 0x1600
	s_add_i32 s64, 0, 0x23000
	v_writelane_b32 v255, s93, 18
	v_writelane_b32 v255, s4, 19
	s_nop 1
	v_writelane_b32 v255, s5, 20
	v_writelane_b32 v255, s98, 21
	s_nop 1
	v_writelane_b32 v255, s99, 22
	v_writelane_b32 v255, s62, 23
	s_nop 1
	v_writelane_b32 v255, s63, 24
	v_writelane_b32 v255, s66, 25
	s_nop 1
	v_writelane_b32 v255, s67, 26
	v_writelane_b32 v255, s70, 27
	s_nop 1
	v_writelane_b32 v255, s71, 28
	v_writelane_b32 v255, s78, 29
	s_nop 1
	v_writelane_b32 v255, s79, 30
	v_writelane_b32 v255, s80, 31
	s_nop 1
	v_writelane_b32 v255, s81, 32
	v_writelane_b32 v255, s86, 33
	s_nop 1
	v_writelane_b32 v255, s87, 34
	v_writelane_b32 v255, s74, 35
	s_nop 1
	v_writelane_b32 v255, s75, 36
	v_writelane_b32 v255, s26, 37
	s_nop 1
	v_writelane_b32 v255, s27, 38
	s_branch .LBB0_162
.LBB0_160:
	s_or_b64 exec, exec, s[4:5]
	s_waitcnt lgkmcnt(0)
	s_barrier

.LBB0_489:
	s_getreg_b32 s6, hwreg(HW_REG_XCC_ID, 0, 4)
	s_waitcnt vmcnt(0)
	s_barrier
	s_and_saveexec_b64 s[4:5], s[74:75]
	s_cbranch_execz .LBB0_541
	v_readlane_b32 s7, v255, 10
	v_readlane_b32 s8, v255, 11
	s_and_b32 s6, s6, 15
	s_lshl_b32 s6, s6, 8
	v_mov_b32_e32 v0, s7
	v_mov_b32_e32 v2, s8
	ds_read_b32 v3, v0
	ds_read_b32 v2, v2
	s_add_i32 s9, s6, 0x1400
	s_add_i32 s10, s6, 0x2400
	v_mov_b32_e32 v0, s9
	v_mov_b32_e32 v4, 1
	s_waitcnt vmcnt(0)
	global_atomic_add v4, v0, v4, s[36:37] sc0
	s_waitcnt lgkmcnt(0)
	v_cvt_f32_u32_e32 v5, v3
	v_rcp_f32_e32 v5, v5
	s_waitcnt vmcnt(0)
	v_cvt_f32_u32_e32 v0, v4
	v_add_f32_e32 v0, 0.5, v0
	v_mul_f32_e32 v0, v0, v5
	v_cvt_u32_f32_e32 v0, v0
	v_add_u32_e32 v5, 1, v0
	v_readfirstlane_b32 s11, v0
	v_mul_lo_u32 v5, v5, v3
	v_add_u32_e32 v4, 1, v4
	v_mov_b32_e32 v0, s10
	v_cmp_ne_u32_e32 vcc, v4, v5
	s_cbranch_vccnz .Lmy_xb0_poll
	buffer_wbl2 sc1
	s_waitcnt vmcnt(0)
	v_mov_b32_e32 v3, 0x3400
	v_mov_b32_e32 v4, 1
	global_atomic_add v4, v3, v4, s[36:37] sc0
	v_cvt_f32_u32_e32 v5, v2
	v_rcp_f32_e32 v5, v5
	s_waitcnt vmcnt(0)
	v_cvt_f32_u32_e32 v3, v4
	v_add_f32_e32 v3, 0.5, v3
	v_mul_f32_e32 v3, v3, v5
	v_cvt_u32_f32_e32 v3, v3
	v_add_u32_e32 v3, 1, v3
	v_mul_lo_u32 v3, v3, v2
	v_add_u32_e32 v4, 1, v4
	v_cmp_ne_u32_e32 vcc, v4, v3
	s_cbranch_vccnz .Lmy_xb0_poll
	v_mov_b32_e32 v4, 1
	v_mov_b32_e32 v3, 0x2400
	global_atomic_add v3, v4, s[36:37]
	v_mov_b32_e32 v3, 0x2500
	global_atomic_add v3, v4, s[36:37]
	v_mov_b32_e32 v3, 0x2600
	global_atomic_add v3, v4, s[36:37]
	v_mov_b32_e32 v3, 0x2700
	global_atomic_add v3, v4, s[36:37]
	v_mov_b32_e32 v3, 0x2800
	global_atomic_add v3, v4, s[36:37]
	v_mov_b32_e32 v3, 0x2900
	global_atomic_add v3, v4, s[36:37]
	v_mov_b32_e32 v3, 0x2a00
	global_atomic_add v3, v4, s[36:37]
	v_mov_b32_e32 v3, 0x2b00
	global_atomic_add v3, v4, s[36:37]
	v_mov_b32_e32 v3, 0x2c00
	global_atomic_add v3, v4, s[36:37]
	v_mov_b32_e32 v3, 0x2d00
	global_atomic_add v3, v4, s[36:37]
	v_mov_b32_e32 v3, 0x2e00
	global_atomic_add v3, v4, s[36:37]
	v_mov_b32_e32 v3, 0x2f00
	global_atomic_add v3, v4, s[36:37]
	v_mov_b32_e32 v3, 0x3000
	global_atomic_add v3, v4, s[36:37]
	v_mov_b32_e32 v3, 0x3100
	global_atomic_add v3, v4, s[36:37]
	v_mov_b32_e32 v3, 0x3200
	global_atomic_add v3, v4, s[36:37]
	v_mov_b32_e32 v3, 0x3300
	global_atomic_add v3, v4, s[36:37]
	v_mov_b32_e32 v3, 0x3500
	global_atomic_add v3, v4, s[36:37]
	s_branch .Lmy_xb0_acq
.Lmy_xb0_poll:
	s_mov_b32 s12, 0
.Lmy_xb0_spin:
	global_load_dword v3, v0, s[36:37] sc1
	s_waitcnt vmcnt(0)
	v_cmp_ne_u32_e32 vcc, s11, v3
	s_cbranch_vccnz .Lmy_xb0_acq
	s_sleep 1
	s_add_i32 s12, s12, 1
	s_cmp_lt_u32 s12, 0x40000
	s_cbranch_scc1 .Lmy_xb0_spin
.Lmy_xb0_acq:
	buffer_inv sc1
	s_waitcnt vmcnt(0)

.LBB0_974:
	s_getreg_b32 s6, hwreg(HW_REG_XCC_ID, 0, 4)
	s_waitcnt vmcnt(0)
	s_waitcnt lgkmcnt(0)
	s_barrier
	s_and_saveexec_b64 s[4:5], s[74:75]
	s_cbranch_execz .LBB0_1026
	v_readlane_b32 s7, v255, 10
	v_readlane_b32 s8, v255, 11
	s_and_b32 s6, s6, 15
	s_lshl_b32 s6, s6, 8
	v_mov_b32_e32 v0, s7
	v_mov_b32_e32 v2, s8
	ds_read_b32 v3, v0
	ds_read_b32 v2, v2
	s_add_i32 s9, s6, 0x1400
	s_add_i32 s10, s6, 0x2400
	v_mov_b32_e32 v0, s9
	v_mov_b32_e32 v4, 1
	s_waitcnt vmcnt(0)
	global_atomic_add v4, v0, v4, s[36:37] sc0
	s_waitcnt lgkmcnt(0)
	v_cvt_f32_u32_e32 v5, v3
	v_rcp_f32_e32 v5, v5
	s_waitcnt vmcnt(0)
	v_cvt_f32_u32_e32 v0, v4
	v_add_f32_e32 v0, 0.5, v0
	v_mul_f32_e32 v0, v0, v5
	v_cvt_u32_f32_e32 v0, v0
	v_add_u32_e32 v5, 1, v0
	v_readfirstlane_b32 s11, v0
	v_mul_lo_u32 v5, v5, v3
	v_add_u32_e32 v4, 1, v4
	v_mov_b32_e32 v0, s10
	v_cmp_ne_u32_e32 vcc, v4, v5
	s_cbranch_vccnz .Lmy_xb2_poll
	buffer_wbl2 sc1
	s_waitcnt vmcnt(0)
	v_mov_b32_e32 v3, 0x3400
	v_mov_b32_e32 v4, 1
	global_atomic_add v4, v3, v4, s[36:37] sc0
	v_cvt_f32_u32_e32 v5, v2
	v_rcp_f32_e32 v5, v5
	s_waitcnt vmcnt(0)
	v_cvt_f32_u32_e32 v3, v4
	v_add_f32_e32 v3, 0.5, v3
	v_mul_f32_e32 v3, v3, v5
	v_cvt_u32_f32_e32 v3, v3
	v_add_u32_e32 v3, 1, v3
	v_mul_lo_u32 v3, v3, v2
	v_add_u32_e32 v4, 1, v4
	v_cmp_ne_u32_e32 vcc, v4, v3
	s_cbranch_vccnz .Lmy_xb2_poll
	v_mov_b32_e32 v4, 1
	v_mov_b32_e32 v3, 0x2400
	global_atomic_add v3, v4, s[36:37]
	v_mov_b32_e32 v3, 0x2500
	global_atomic_add v3, v4, s[36:37]
	v_mov_b32_e32 v3, 0x2600
	global_atomic_add v3, v4, s[36:37]
	v_mov_b32_e32 v3, 0x2700
	global_atomic_add v3, v4, s[36:37]
	v_mov_b32_e32 v3, 0x2800
	global_atomic_add v3, v4, s[36:37]
	v_mov_b32_e32 v3, 0x2900
	global_atomic_add v3, v4, s[36:37]
	v_mov_b32_e32 v3, 0x2a00
	global_atomic_add v3, v4, s[36:37]
	v_mov_b32_e32 v3, 0x2b00
	global_atomic_add v3, v4, s[36:37]
	v_mov_b32_e32 v3, 0x2c00
	global_atomic_add v3, v4, s[36:37]
	v_mov_b32_e32 v3, 0x2d00
	global_atomic_add v3, v4, s[36:37]
	v_mov_b32_e32 v3, 0x2e00
	global_atomic_add v3, v4, s[36:37]
	v_mov_b32_e32 v3, 0x2f00
	global_atomic_add v3, v4, s[36:37]
	v_mov_b32_e32 v3, 0x3000
	global_atomic_add v3, v4, s[36:37]
	v_mov_b32_e32 v3, 0x3100
	global_atomic_add v3, v4, s[36:37]
	v_mov_b32_e32 v3, 0x3200
	global_atomic_add v3, v4, s[36:37]
	v_mov_b32_e32 v3, 0x3300
	global_atomic_add v3, v4, s[36:37]
	v_mov_b32_e32 v3, 0x3500
	global_atomic_add v3, v4, s[36:37]
	s_branch .Lmy_xb2_acq

.LBB0_1186:
	s_cmp_eq_u32 s40, 7
	v_readlane_b32 s26, v255, 37
	v_readlane_b32 s27, v255, 38
	s_cbranch_scc1 .LBB0_161
	s_getreg_b32 s6, hwreg(HW_REG_XCC_ID, 0, 4)
	s_waitcnt vmcnt(0)
	s_barrier
	s_and_saveexec_b64 s[4:5], s[74:75]
	s_cbranch_execz .LBB0_160
	v_readlane_b32 s7, v255, 10
	v_readlane_b32 s8, v255, 11
	s_and_b32 s6, s6, 15
	s_lshl_b32 s6, s6, 8
	v_mov_b32_e32 v0, s7
	v_mov_b32_e32 v2, s8
	ds_read_b32 v3, v0
	ds_read_b32 v2, v2
	s_add_i32 s9, s6, 0x1400
	s_add_i32 s10, s6, 0x2400
	v_mov_b32_e32 v0, s9
	v_mov_b32_e32 v4, 1
	s_waitcnt vmcnt(0)
	global_atomic_add v4, v0, v4, s[36:37] sc0
	s_waitcnt lgkmcnt(0)
	v_cvt_f32_u32_e32 v5, v3
	v_rcp_f32_e32 v5, v5
	s_waitcnt vmcnt(0)
	v_cvt_f32_u32_e32 v0, v4
	v_add_f32_e32 v0, 0.5, v0
	v_mul_f32_e32 v0, v0, v5
	v_cvt_u32_f32_e32 v0, v0
	v_add_u32_e32 v5, 1, v0
	v_readfirstlane_b32 s11, v0
	v_mul_lo_u32 v5, v5, v3
	v_add_u32_e32 v4, 1, v4
	v_mov_b32_e32 v0, s10
	v_cmp_ne_u32_e32 vcc, v4, v5
	s_cbranch_vccnz .Lmy_xb3_poll
	buffer_wbl2 sc1
	s_waitcnt vmcnt(0)
	v_mov_b32_e32 v3, 0x3400
	v_mov_b32_e32 v4, 1
	global_atomic_add v4, v3, v4, s[36:37] sc0
	v_cvt_f32_u32_e32 v5, v2
	v_rcp_f32_e32 v5, v5
	s_waitcnt vmcnt(0)
	v_cvt_f32_u32_e32 v3, v4
	v_add_f32_e32 v3, 0.5, v3
	v_mul_f32_e32 v3, v3, v5
	v_cvt_u32_f32_e32 v3, v3
	v_add_u32_e32 v3, 1, v3
	v_mul_lo_u32 v3, v3, v2
	v_add_u32_e32 v4, 1, v4
	v_cmp_ne_u32_e32 vcc, v4, v3
	s_cbranch_vccnz .Lmy_xb3_poll
	v_mov_b32_e32 v4, 1
	v_mov_b32_e32 v3, 0x2400
	global_atomic_add v3, v4, s[36:37]
	v_mov_b32_e32 v3, 0x2500
	global_atomic_add v3, v4, s[36:37]
	v_mov_b32_e32 v3, 0x2600
	global_atomic_add v3, v4, s[36:37]
	v_mov_b32_e32 v3, 0x2700
	global_atomic_add v3, v4, s[36:37]
	v_mov_b32_e32 v3, 0x2800
	global_atomic_add v3, v4, s[36:37]
	v_mov_b32_e32 v3, 0x2900
	global_atomic_add v3, v4, s[36:37]
	v_mov_b32_e32 v3, 0x2a00
	global_atomic_add v3, v4, s[36:37]
	v_mov_b32_e32 v3, 0x2b00
	global_atomic_add v3, v4, s[36:37]
	v_mov_b32_e32 v3, 0x2c00
	global_atomic_add v3, v4, s[36:37]
	v_mov_b32_e32 v3, 0x2d00
	global_atomic_add v3, v4, s[36:37]
	v_mov_b32_e32 v3, 0x2e00
	global_atomic_add v3, v4, s[36:37]
	v_mov_b32_e32 v3, 0x2f00
	global_atomic_add v3, v4, s[36:37]
	v_mov_b32_e32 v3, 0x3000
	global_atomic_add v3, v4, s[36:37]
	v_mov_b32_e32 v3, 0x3100
	global_atomic_add v3, v4, s[36:37]
	v_mov_b32_e32 v3, 0x3200
	global_atomic_add v3, v4, s[36:37]
	v_mov_b32_e32 v3, 0x3300
	global_atomic_add v3, v4, s[36:37]
	v_mov_b32_e32 v3, 0x3500
	global_atomic_add v3, v4, s[36:37]
	s_branch .Lmy_xb3_acq

.Lmy_xb3_acq:
	buffer_inv sc1
	s_waitcnt vmcnt(0)
	s_branch .LBB0_160
